# gemm_out: 256x256 tiles for 16 panels per XCD group, the 17th panel of the first layer by all 32 workgroups of the group (32 columns each)
# baseline (speedup 1.0000x reference)
.Lgo_end:
	s_mov_b64 exec, -1
	s_waitcnt vmcnt(0)
	s_barrier
	s_cmp_lg_u64 s[90:91], 0
	s_cbranch_scc1 .Lgo_skip
	v_and_b32_e32 v37, 31, v143
	v_bfe_u32 v38, v143, 5, 1
	v_lshrrev_b32_e32 v32, 6, v143
	v_lshl_add_u32 v32, v32, 5, v37
	v_lshlrev_b32_e32 v32, 11, v32
	v_lshl_add_u32 v33, v38, 5, v32
	v_lshl_add_u32 v32, v38, 4, v32
	v_lshlrev_b32_e32 v34, 4, v143
	v_lshrrev_b32_e32 v35, 7, v143
	v_mul_u32_u24_e32 v35, 2064, v35
	v_and_b32_e32 v36, 127, v143
	v_lshl_add_u32 v35, v36, 4, v35
	v_mul_u32_u24_e32 v36, 2064, v37
	v_lshl_add_u32 v36, v38, 4, v36
	v_readlane_b32 s0, v253, 0
	s_and_b32 s1, s0, 7
	s_lshr_b32 s0, s0, 3
	s_mul_i32 s1, s1, 17
	s_add_u32 s1, s1, 16
	s_lshl_b32 s1, s1, 19
	s_lshl_b32 s12, s0, 16
	s_lshl_b32 s13, s74, 21
	s_add_u32 s12, s12, s13
	s_add_u32 s12, s12, 0xc40000
	s_add_u32 s4, s50, s12
	s_addc_u32 s5, s51, 0
	s_add_u32 s12, s1, 0x18bd000
	s_add_u32 s6, s50, s12
	s_addc_u32 s7, s51, 0
	s_lshl_b32 s0, s0, 6
	s_add_u32 s12, s1, s0
	s_add_u32 s12, s12, 0x108dd000
	s_add_u32 s8, s50, s12
	s_addc_u32 s9, s51, 0
	s_mov_b64 s[10:11], s[4:5]
	global_load_dwordx4 v[16:19], v34, s[10:11]
	s_add_u32 s10, s10, 0x2000
	s_addc_u32 s11, s11, 0
	global_load_dwordx4 v[20:23], v34, s[10:11]
	s_add_u32 s10, s10, 0x2000
	s_addc_u32 s11, s11, 0
	global_load_dwordx4 v[24:27], v34, s[10:11]
	s_add_u32 s10, s10, 0x2000
	s_addc_u32 s11, s11, 0
	global_load_dwordx4 v[28:31], v34, s[10:11]
	s_add_u32 s10, s10, 0x2000
	s_addc_u32 s11, s11, 0
	global_load_dwordx4 v[220:223], v34, s[10:11]
	s_add_u32 s10, s10, 0x2000
	s_addc_u32 s11, s11, 0
	global_load_dwordx4 v[224:227], v34, s[10:11]
	s_add_u32 s10, s10, 0x2000
	s_addc_u32 s11, s11, 0
	global_load_dwordx4 v[228:231], v34, s[10:11]
	s_add_u32 s10, s10, 0x2000
	s_addc_u32 s11, s11, 0
	global_load_dwordx4 v[240:243], v34, s[10:11]
	global_load_dwordx4 v[48:51], v32, s[6:7] offset:0
	global_load_dwordx4 v[52:55], v32, s[6:7] offset:32
	global_load_dwordx4 v[56:59], v32, s[6:7] offset:64
	global_load_dwordx4 v[60:63], v32, s[6:7] offset:96
	global_load_dwordx4 v[64:67], v32, s[6:7] offset:128
	global_load_dwordx4 v[68:71], v32, s[6:7] offset:160
	global_load_dwordx4 v[72:75], v32, s[6:7] offset:192
	global_load_dwordx4 v[76:79], v32, s[6:7] offset:224
	global_load_dwordx4 v[96:99], v32, s[6:7] offset:256
	global_load_dwordx4 v[100:103], v32, s[6:7] offset:288
	global_load_dwordx4 v[104:107], v32, s[6:7] offset:320
	global_load_dwordx4 v[108:111], v32, s[6:7] offset:352
	global_load_dwordx4 v[112:115], v32, s[6:7] offset:384
	global_load_dwordx4 v[116:119], v32, s[6:7] offset:416
	global_load_dwordx4 v[120:123], v32, s[6:7] offset:448
	global_load_dwordx4 v[124:127], v32, s[6:7] offset:480
	global_load_dwordx4 v[188:191], v32, s[6:7] offset:512
	global_load_dwordx4 v[192:195], v32, s[6:7] offset:544
	global_load_dwordx4 v[196:199], v32, s[6:7] offset:576
	global_load_dwordx4 v[200:203], v32, s[6:7] offset:608
	global_load_dwordx4 v[204:207], v32, s[6:7] offset:640
	global_load_dwordx4 v[208:211], v32, s[6:7] offset:672
	global_load_dwordx4 v[212:215], v32, s[6:7] offset:704
	global_load_dwordx4 v[216:219], v32, s[6:7] offset:736
	s_waitcnt vmcnt(24)
	ds_write_b128 v35, v[16:19] offset:0
	ds_write_b128 v35, v[20:23] offset:8256
	ds_write_b128 v35, v[24:27] offset:16512
	ds_write_b128 v35, v[28:31] offset:24768
	ds_write_b128 v35, v[220:223] offset:33024
	ds_write_b128 v35, v[224:227] offset:41280
	ds_write_b128 v35, v[228:231] offset:49536
	ds_write_b128 v35, v[240:243] offset:57792
	s_waitcnt lgkmcnt(0)
	s_barrier
	ds_read_b128 v[130:133], v36 offset:0
	ds_read_b128 v[134:137], v36 offset:32
	ds_read_b128 v[138:141], v36 offset:64
	ds_read_b128 v[144:147], v36 offset:96
	ds_read_b128 v[148:151], v36 offset:128
	ds_read_b128 v[152:155], v36 offset:160
	ds_read_b128 v[160:163], v36 offset:192
	ds_read_b128 v[164:167], v36 offset:224
	s_waitcnt vmcnt(23) lgkmcnt(7)
	v_mfma_f32_32x32x16_bf16 v[0:15], v[130:133], v[48:51], 0
	ds_read_b128 v[130:133], v36 offset:256
	global_load_dwordx4 v[48:51], v32, s[6:7] offset:768
	s_waitcnt vmcnt(23) lgkmcnt(7)
	v_mfma_f32_32x32x16_bf16 v[0:15], v[134:137], v[52:55], v[0:15]
	ds_read_b128 v[134:137], v36 offset:288
	global_load_dwordx4 v[52:55], v32, s[6:7] offset:800
	s_waitcnt vmcnt(23) lgkmcnt(7)
	v_mfma_f32_32x32x16_bf16 v[0:15], v[138:141], v[56:59], v[0:15]
	ds_read_b128 v[138:141], v36 offset:320
	global_load_dwordx4 v[56:59], v32, s[6:7] offset:832
	s_waitcnt vmcnt(23) lgkmcnt(7)
	v_mfma_f32_32x32x16_bf16 v[0:15], v[144:147], v[60:63], v[0:15]
	ds_read_b128 v[144:147], v36 offset:352
	global_load_dwordx4 v[60:63], v32, s[6:7] offset:864
	s_waitcnt vmcnt(23) lgkmcnt(7)
	v_mfma_f32_32x32x16_bf16 v[0:15], v[148:151], v[64:67], v[0:15]
	ds_read_b128 v[148:151], v36 offset:384
	global_load_dwordx4 v[64:67], v32, s[6:7] offset:896
	s_waitcnt vmcnt(23) lgkmcnt(7)
	v_mfma_f32_32x32x16_bf16 v[0:15], v[152:155], v[68:71], v[0:15]
	ds_read_b128 v[152:155], v36 offset:416
	global_load_dwordx4 v[68:71], v32, s[6:7] offset:928
	s_waitcnt vmcnt(23) lgkmcnt(7)
	v_mfma_f32_32x32x16_bf16 v[0:15], v[160:163], v[72:75], v[0:15]
	ds_read_b128 v[160:163], v36 offset:448
	global_load_dwordx4 v[72:75], v32, s[6:7] offset:960
	s_waitcnt vmcnt(23) lgkmcnt(7)
	v_mfma_f32_32x32x16_bf16 v[0:15], v[164:167], v[76:79], v[0:15]
	ds_read_b128 v[164:167], v36 offset:480
	global_load_dwordx4 v[76:79], v32, s[6:7] offset:992
	s_waitcnt vmcnt(23) lgkmcnt(7)
	v_mfma_f32_32x32x16_bf16 v[0:15], v[130:133], v[96:99], v[0:15]
	ds_read_b128 v[130:133], v36 offset:512
	global_load_dwordx4 v[96:99], v32, s[6:7] offset:1024
	s_waitcnt vmcnt(23) lgkmcnt(7)
	v_mfma_f32_32x32x16_bf16 v[0:15], v[134:137], v[100:103], v[0:15]
	ds_read_b128 v[134:137], v36 offset:544
	global_load_dwordx4 v[100:103], v32, s[6:7] offset:1056
	s_waitcnt vmcnt(23) lgkmcnt(7)
	v_mfma_f32_32x32x16_bf16 v[0:15], v[138:141], v[104:107], v[0:15]
	ds_read_b128 v[138:141], v36 offset:576
	global_load_dwordx4 v[104:107], v32, s[6:7] offset:1088
	s_waitcnt vmcnt(23) lgkmcnt(7)
	v_mfma_f32_32x32x16_bf16 v[0:15], v[144:147], v[108:111], v[0:15]
	ds_read_b128 v[144:147], v36 offset:608
	global_load_dwordx4 v[108:111], v32, s[6:7] offset:1120
	s_waitcnt vmcnt(23) lgkmcnt(7)
	v_mfma_f32_32x32x16_bf16 v[0:15], v[148:151], v[112:115], v[0:15]
	ds_read_b128 v[148:151], v36 offset:640
	global_load_dwordx4 v[112:115], v32, s[6:7] offset:1152
	s_waitcnt vmcnt(23) lgkmcnt(7)
	v_mfma_f32_32x32x16_bf16 v[0:15], v[152:155], v[116:119], v[0:15]
	ds_read_b128 v[152:155], v36 offset:672
	global_load_dwordx4 v[116:119], v32, s[6:7] offset:1184
	s_waitcnt vmcnt(23) lgkmcnt(7)
	v_mfma_f32_32x32x16_bf16 v[0:15], v[160:163], v[120:123], v[0:15]
	ds_read_b128 v[160:163], v36 offset:704
	global_load_dwordx4 v[120:123], v32, s[6:7] offset:1216
	s_waitcnt vmcnt(23) lgkmcnt(7)
	v_mfma_f32_32x32x16_bf16 v[0:15], v[164:167], v[124:127], v[0:15]
	ds_read_b128 v[164:167], v36 offset:736
	global_load_dwordx4 v[124:127], v32, s[6:7] offset:1248
	s_waitcnt vmcnt(23) lgkmcnt(7)
	v_mfma_f32_32x32x16_bf16 v[0:15], v[130:133], v[188:191], v[0:15]
	ds_read_b128 v[130:133], v36 offset:768
	global_load_dwordx4 v[188:191], v32, s[6:7] offset:1280
	s_waitcnt vmcnt(23) lgkmcnt(7)
	v_mfma_f32_32x32x16_bf16 v[0:15], v[134:137], v[192:195], v[0:15]
	ds_read_b128 v[134:137], v36 offset:800
	global_load_dwordx4 v[192:195], v32, s[6:7] offset:1312
	s_waitcnt vmcnt(23) lgkmcnt(7)
	v_mfma_f32_32x32x16_bf16 v[0:15], v[138:141], v[196:199], v[0:15]
	ds_read_b128 v[138:141], v36 offset:832
	global_load_dwordx4 v[196:199], v32, s[6:7] offset:1344
	s_waitcnt vmcnt(23) lgkmcnt(7)
	v_mfma_f32_32x32x16_bf16 v[0:15], v[144:147], v[200:203], v[0:15]
	ds_read_b128 v[144:147], v36 offset:864
	global_load_dwordx4 v[200:203], v32, s[6:7] offset:1376
	s_waitcnt vmcnt(23) lgkmcnt(7)
	v_mfma_f32_32x32x16_bf16 v[0:15], v[148:151], v[204:207], v[0:15]
	ds_read_b128 v[148:151], v36 offset:896
	global_load_dwordx4 v[204:207], v32, s[6:7] offset:1408
	s_waitcnt vmcnt(23) lgkmcnt(7)
	v_mfma_f32_32x32x16_bf16 v[0:15], v[152:155], v[208:211], v[0:15]
	ds_read_b128 v[152:155], v36 offset:928
	global_load_dwordx4 v[208:211], v32, s[6:7] offset:1440
	s_waitcnt vmcnt(23) lgkmcnt(7)
	v_mfma_f32_32x32x16_bf16 v[0:15], v[160:163], v[212:215], v[0:15]
	ds_read_b128 v[160:163], v36 offset:960
	global_load_dwordx4 v[212:215], v32, s[6:7] offset:1472
	s_waitcnt vmcnt(23) lgkmcnt(7)
	v_mfma_f32_32x32x16_bf16 v[0:15], v[164:167], v[216:219], v[0:15]
	ds_read_b128 v[164:167], v36 offset:992
	global_load_dwordx4 v[216:219], v32, s[6:7] offset:1504
	s_waitcnt vmcnt(23) lgkmcnt(7)
	v_mfma_f32_32x32x16_bf16 v[0:15], v[130:133], v[48:51], v[0:15]
	ds_read_b128 v[130:133], v36 offset:1024
	global_load_dwordx4 v[48:51], v32, s[6:7] offset:1536
	s_waitcnt vmcnt(23) lgkmcnt(7)
	v_mfma_f32_32x32x16_bf16 v[0:15], v[134:137], v[52:55], v[0:15]
	ds_read_b128 v[134:137], v36 offset:1056
	global_load_dwordx4 v[52:55], v32, s[6:7] offset:1568
	s_waitcnt vmcnt(23) lgkmcnt(7)
	v_mfma_f32_32x32x16_bf16 v[0:15], v[138:141], v[56:59], v[0:15]
	ds_read_b128 v[138:141], v36 offset:1088
	global_load_dwordx4 v[56:59], v32, s[6:7] offset:1600
	s_waitcnt vmcnt(23) lgkmcnt(7)
	v_mfma_f32_32x32x16_bf16 v[0:15], v[144:147], v[60:63], v[0:15]
	ds_read_b128 v[144:147], v36 offset:1120
	global_load_dwordx4 v[60:63], v32, s[6:7] offset:1632
	s_waitcnt vmcnt(23) lgkmcnt(7)
	v_mfma_f32_32x32x16_bf16 v[0:15], v[148:151], v[64:67], v[0:15]
	ds_read_b128 v[148:151], v36 offset:1152
	global_load_dwordx4 v[64:67], v32, s[6:7] offset:1664
	s_waitcnt vmcnt(23) lgkmcnt(7)
	v_mfma_f32_32x32x16_bf16 v[0:15], v[152:155], v[68:71], v[0:15]
	ds_read_b128 v[152:155], v36 offset:1184
	global_load_dwordx4 v[68:71], v32, s[6:7] offset:1696
	s_waitcnt vmcnt(23) lgkmcnt(7)
	v_mfma_f32_32x32x16_bf16 v[0:15], v[160:163], v[72:75], v[0:15]
	ds_read_b128 v[160:163], v36 offset:1216
	global_load_dwordx4 v[72:75], v32, s[6:7] offset:1728
	s_waitcnt vmcnt(23) lgkmcnt(7)
	v_mfma_f32_32x32x16_bf16 v[0:15], v[164:167], v[76:79], v[0:15]
	ds_read_b128 v[164:167], v36 offset:1248
	global_load_dwordx4 v[76:79], v32, s[6:7] offset:1760
	s_waitcnt vmcnt(23) lgkmcnt(7)
	v_mfma_f32_32x32x16_bf16 v[0:15], v[130:133], v[96:99], v[0:15]
	ds_read_b128 v[130:133], v36 offset:1280
	global_load_dwordx4 v[96:99], v32, s[6:7] offset:1792
	s_waitcnt vmcnt(23) lgkmcnt(7)
	v_mfma_f32_32x32x16_bf16 v[0:15], v[134:137], v[100:103], v[0:15]
	ds_read_b128 v[134:137], v36 offset:1312
	global_load_dwordx4 v[100:103], v32, s[6:7] offset:1824
	s_waitcnt vmcnt(23) lgkmcnt(7)
	v_mfma_f32_32x32x16_bf16 v[0:15], v[138:141], v[104:107], v[0:15]
	ds_read_b128 v[138:141], v36 offset:1344
	global_load_dwordx4 v[104:107], v32, s[6:7] offset:1856
	s_waitcnt vmcnt(23) lgkmcnt(7)
	v_mfma_f32_32x32x16_bf16 v[0:15], v[144:147], v[108:111], v[0:15]
	ds_read_b128 v[144:147], v36 offset:1376
	global_load_dwordx4 v[108:111], v32, s[6:7] offset:1888
	s_waitcnt vmcnt(23) lgkmcnt(7)
	v_mfma_f32_32x32x16_bf16 v[0:15], v[148:151], v[112:115], v[0:15]
	ds_read_b128 v[148:151], v36 offset:1408
	global_load_dwordx4 v[112:115], v32, s[6:7] offset:1920
	s_waitcnt vmcnt(23) lgkmcnt(7)
	v_mfma_f32_32x32x16_bf16 v[0:15], v[152:155], v[116:119], v[0:15]
	ds_read_b128 v[152:155], v36 offset:1440
	global_load_dwordx4 v[116:119], v32, s[6:7] offset:1952
	s_waitcnt vmcnt(23) lgkmcnt(7)
	v_mfma_f32_32x32x16_bf16 v[0:15], v[160:163], v[120:123], v[0:15]
	ds_read_b128 v[160:163], v36 offset:1472
	global_load_dwordx4 v[120:123], v32, s[6:7] offset:1984
	s_waitcnt vmcnt(23) lgkmcnt(7)
	v_mfma_f32_32x32x16_bf16 v[0:15], v[164:167], v[124:127], v[0:15]
	ds_read_b128 v[164:167], v36 offset:1504
	global_load_dwordx4 v[124:127], v32, s[6:7] offset:2016
	s_waitcnt vmcnt(23) lgkmcnt(7)
	v_mfma_f32_32x32x16_bf16 v[0:15], v[130:133], v[188:191], v[0:15]
	ds_read_b128 v[130:133], v36 offset:1536
	s_waitcnt vmcnt(22) lgkmcnt(7)
	v_mfma_f32_32x32x16_bf16 v[0:15], v[134:137], v[192:195], v[0:15]
	ds_read_b128 v[134:137], v36 offset:1568
	s_waitcnt vmcnt(21) lgkmcnt(7)
	v_mfma_f32_32x32x16_bf16 v[0:15], v[138:141], v[196:199], v[0:15]
	ds_read_b128 v[138:141], v36 offset:1600
	s_waitcnt vmcnt(20) lgkmcnt(7)
	v_mfma_f32_32x32x16_bf16 v[0:15], v[144:147], v[200:203], v[0:15]
	ds_read_b128 v[144:147], v36 offset:1632
	s_waitcnt vmcnt(19) lgkmcnt(7)
	v_mfma_f32_32x32x16_bf16 v[0:15], v[148:151], v[204:207], v[0:15]
	ds_read_b128 v[148:151], v36 offset:1664
	s_waitcnt vmcnt(18) lgkmcnt(7)
	v_mfma_f32_32x32x16_bf16 v[0:15], v[152:155], v[208:211], v[0:15]
	ds_read_b128 v[152:155], v36 offset:1696
	s_waitcnt vmcnt(17) lgkmcnt(7)
	v_mfma_f32_32x32x16_bf16 v[0:15], v[160:163], v[212:215], v[0:15]
	ds_read_b128 v[160:163], v36 offset:1728
	s_waitcnt vmcnt(16) lgkmcnt(7)
	v_mfma_f32_32x32x16_bf16 v[0:15], v[164:167], v[216:219], v[0:15]
	ds_read_b128 v[164:167], v36 offset:1760
	s_waitcnt vmcnt(15) lgkmcnt(7)
	v_mfma_f32_32x32x16_bf16 v[0:15], v[130:133], v[48:51], v[0:15]
	ds_read_b128 v[130:133], v36 offset:1792
	s_waitcnt vmcnt(14) lgkmcnt(7)
	v_mfma_f32_32x32x16_bf16 v[0:15], v[134:137], v[52:55], v[0:15]
	ds_read_b128 v[134:137], v36 offset:1824
	s_waitcnt vmcnt(13) lgkmcnt(7)
	v_mfma_f32_32x32x16_bf16 v[0:15], v[138:141], v[56:59], v[0:15]
	ds_read_b128 v[138:141], v36 offset:1856
	s_waitcnt vmcnt(12) lgkmcnt(7)
	v_mfma_f32_32x32x16_bf16 v[0:15], v[144:147], v[60:63], v[0:15]
	ds_read_b128 v[144:147], v36 offset:1888
	s_waitcnt vmcnt(11) lgkmcnt(7)
	v_mfma_f32_32x32x16_bf16 v[0:15], v[148:151], v[64:67], v[0:15]
	ds_read_b128 v[148:151], v36 offset:1920
	s_waitcnt vmcnt(10) lgkmcnt(7)
	v_mfma_f32_32x32x16_bf16 v[0:15], v[152:155], v[68:71], v[0:15]
	ds_read_b128 v[152:155], v36 offset:1952
	s_waitcnt vmcnt(9) lgkmcnt(7)
	v_mfma_f32_32x32x16_bf16 v[0:15], v[160:163], v[72:75], v[0:15]
	ds_read_b128 v[160:163], v36 offset:1984
	s_waitcnt vmcnt(8) lgkmcnt(7)
	v_mfma_f32_32x32x16_bf16 v[0:15], v[164:167], v[76:79], v[0:15]
	ds_read_b128 v[164:167], v36 offset:2016
	s_waitcnt vmcnt(7) lgkmcnt(7)
	v_mfma_f32_32x32x16_bf16 v[0:15], v[130:133], v[96:99], v[0:15]
	s_waitcnt vmcnt(6) lgkmcnt(6)
	v_mfma_f32_32x32x16_bf16 v[0:15], v[134:137], v[100:103], v[0:15]
	s_waitcnt vmcnt(5) lgkmcnt(5)
	v_mfma_f32_32x32x16_bf16 v[0:15], v[138:141], v[104:107], v[0:15]
	s_waitcnt vmcnt(4) lgkmcnt(4)
	v_mfma_f32_32x32x16_bf16 v[0:15], v[144:147], v[108:111], v[0:15]
	s_waitcnt vmcnt(3) lgkmcnt(3)
	v_mfma_f32_32x32x16_bf16 v[0:15], v[148:151], v[112:115], v[0:15]
	s_waitcnt vmcnt(2) lgkmcnt(2)
	v_mfma_f32_32x32x16_bf16 v[0:15], v[152:155], v[116:119], v[0:15]
	s_waitcnt vmcnt(1) lgkmcnt(1)
	v_mfma_f32_32x32x16_bf16 v[0:15], v[160:163], v[120:123], v[0:15]
	s_waitcnt vmcnt(0) lgkmcnt(0)
	v_mfma_f32_32x32x16_bf16 v[0:15], v[164:167], v[124:127], v[0:15]
	s_nop 7
	s_nop 7
	v_cvt_pk_bf16_f32 v244, v0, v1
	v_cvt_pk_bf16_f32 v245, v2, v3
	v_cvt_pk_bf16_f32 v248, v4, v5
	v_cvt_pk_bf16_f32 v249, v6, v7
	v_cvt_pk_bf16_f32 v246, v8, v9
	v_cvt_pk_bf16_f32 v247, v10, v11
	v_cvt_pk_bf16_f32 v250, v12, v13
	v_cvt_pk_bf16_f32 v251, v14, v15
	s_nop 1
	v_permlane32_swap_b32_e32 v244, v246
	v_permlane32_swap_b32_e32 v245, v247
	v_permlane32_swap_b32_e32 v248, v250
	v_permlane32_swap_b32_e32 v249, v251
	global_store_dwordx4 v33, v[244:247], s[8:9]
	global_store_dwordx4 v33, v[248:251], s[8:9] offset:16
	s_waitcnt vmcnt(0)
	s_barrier
